# phase 10 (RWKV in-proj, register-staged A) K-loop: fragment reads reordered, ks=1 reads prefetched into second register set, counted waits
# speedup vs baseline: 1.0043x; 1.0043x over previous
.LBB0_1055:
	s_lshl_b32 s58, s80, 1
	s_add_i32 s58, s58, 32
	v_lshl_add_u32 v80, v147, 1, s58
	v_lshl_add_u32 v105, v148, 1, s58
	v_add_u32_e32 v132, v80, v165
	v_add_u32_e32 v133, v105, v165
	ds_read_b128 v[172:175], v132
	ds_read_b128 v[182:185], v133 offset:16384
	ds_read_b128 v[186:189], v133 offset:18432
	ds_read_b128 v[198:201], v133 offset:20480
	ds_read_b128 v[202:205], v133 offset:22528
	ds_read_b128 v[176:179], v132 offset:2048
	ds_read_b128 v[190:193], v132 offset:4096
	ds_read_b128 v[194:197], v132 offset:6144
	v_add_u32_e32 v238, v80, v166
	v_add_u32_e32 v239, v105, v166
	ds_read_b128 v[206:209], v238
	ds_read_b128 v[210:213], v239 offset:16384
	ds_read_b128 v[214:217], v239 offset:18432
	ds_read_b128 v[218:221], v239 offset:20480
	ds_read_b128 v[222:225], v239 offset:22528
	ds_read_b128 v[226:229], v238 offset:2048
	ds_read_b128 v[230:233], v238 offset:4096
	ds_read_b128 v[234:237], v238 offset:6144
	s_setprio 1
	s_waitcnt lgkmcnt(11)
	v_mfma_f32_16x16x32_bf16 v[60:63], v[172:175], v[182:185], v[60:63]
	v_mfma_f32_16x16x32_bf16 v[56:59], v[172:175], v[186:189], v[56:59]
	v_mfma_f32_16x16x32_bf16 v[52:55], v[172:175], v[198:201], v[52:55]
	v_mfma_f32_16x16x32_bf16 v[48:51], v[172:175], v[202:205], v[48:51]
	s_waitcnt lgkmcnt(10)
	v_mfma_f32_16x16x32_bf16 v[44:47], v[176:179], v[182:185], v[44:47]
	v_mfma_f32_16x16x32_bf16 v[40:43], v[176:179], v[186:189], v[40:43]
	v_mfma_f32_16x16x32_bf16 v[36:39], v[176:179], v[198:201], v[36:39]
	v_mfma_f32_16x16x32_bf16 v[32:35], v[176:179], v[202:205], v[32:35]
	s_waitcnt lgkmcnt(9)
	v_mfma_f32_16x16x32_bf16 v[28:31], v[190:193], v[182:185], v[28:31]
	v_mfma_f32_16x16x32_bf16 v[24:27], v[190:193], v[186:189], v[24:27]
	v_mfma_f32_16x16x32_bf16 v[20:23], v[190:193], v[198:201], v[20:23]
	v_mfma_f32_16x16x32_bf16 v[16:19], v[190:193], v[202:205], v[16:19]
	s_waitcnt lgkmcnt(8)
	v_mfma_f32_16x16x32_bf16 v[12:15], v[194:197], v[182:185], v[12:15]
	v_mfma_f32_16x16x32_bf16 v[8:11], v[194:197], v[186:189], v[8:11]
	v_mfma_f32_16x16x32_bf16 v[4:7], v[194:197], v[198:201], v[4:7]
	v_mfma_f32_16x16x32_bf16 v[0:3], v[194:197], v[202:205], v[0:3]
	s_waitcnt lgkmcnt(3)
	v_mfma_f32_16x16x32_bf16 v[60:63], v[206:209], v[210:213], v[60:63]
	v_mfma_f32_16x16x32_bf16 v[56:59], v[206:209], v[214:217], v[56:59]
	v_mfma_f32_16x16x32_bf16 v[52:55], v[206:209], v[218:221], v[52:55]
	v_mfma_f32_16x16x32_bf16 v[48:51], v[206:209], v[222:225], v[48:51]
	s_waitcnt lgkmcnt(2)
	v_mfma_f32_16x16x32_bf16 v[44:47], v[226:229], v[210:213], v[44:47]
	v_mfma_f32_16x16x32_bf16 v[40:43], v[226:229], v[214:217], v[40:43]
	v_mfma_f32_16x16x32_bf16 v[36:39], v[226:229], v[218:221], v[36:39]
	v_mfma_f32_16x16x32_bf16 v[32:35], v[226:229], v[222:225], v[32:35]
	s_waitcnt lgkmcnt(1)
	v_mfma_f32_16x16x32_bf16 v[28:31], v[230:233], v[210:213], v[28:31]
	v_mfma_f32_16x16x32_bf16 v[24:27], v[230:233], v[214:217], v[24:27]
	v_mfma_f32_16x16x32_bf16 v[20:23], v[230:233], v[218:221], v[20:23]
	v_mfma_f32_16x16x32_bf16 v[16:19], v[230:233], v[222:225], v[16:19]
	s_waitcnt lgkmcnt(0)
	v_mfma_f32_16x16x32_bf16 v[12:15], v[234:237], v[210:213], v[12:15]
	v_mfma_f32_16x16x32_bf16 v[8:11], v[234:237], v[214:217], v[8:11]
	v_mfma_f32_16x16x32_bf16 v[4:7], v[234:237], v[218:221], v[4:7]
	v_mfma_f32_16x16x32_bf16 v[0:3], v[234:237], v[222:225], v[0:3]
	s_setprio 0
	s_addk_i32 s79, 0x4000
	s_add_u32 s50, s50, 0x80
	s_addc_u32 s51, s51, 0
	v_add3_u32 v80, s48, v167, v145
	s_cmpk_eq_i32 s50, 0x780
	v_lshl_add_u64 v[110:111], v[110:111], 0, s[44:45]
	s_waitcnt vmcnt(0)
	ds_write_b128 v80, v[64:67]
	ds_write_b128 v80, v[68:71] offset:4096
	ds_write_b128 v80, v[72:75] offset:8192
	ds_write_b128 v80, v[76:79] offset:12288
	s_waitcnt lgkmcnt(0)
	s_barrier
	s_cbranch_scc1 .LBB0_1135
